# final RMSNorm loop software-pipelined (next iteration loads before current math), on top of prep+glr wait fixes
# baseline (speedup 1.0000x reference)
.LBB0_1286:
	v_lshrrev_b64 v[14:15], 6, v[4:5]
	v_and_b32_e32 v15, 0x3ffffff, v15
	v_and_b32_e32 v14, -4, v14
	v_lshl_add_u64 v[16:17], s[8:9], 0, v[4:5]
	v_lshl_add_u64 v[14:15], s[6:7], 0, v[14:15]
	v_lshl_add_u64 v[20:21], s[30:31], 0, v[4:5]
	v_lshl_add_u64 v[24:25], s[12:13], 0, v[4:5]
	v_lshrrev_b64 v[16:17], 6, v[16:17]
	global_load_dword v11, v[14:15], off
	v_lshrrev_b64 v[20:21], 6, v[20:21]
	v_lshrrev_b64 v[24:25], 6, v[24:25]
	v_and_b32_e32 v17, 0x3ffffff, v17
	v_and_b32_e32 v16, -4, v16
	v_lshl_add_u64 v[18:19], v[6:7], 0, s[20:21]
	v_lshl_add_u64 v[22:23], v[6:7], 0, s[14:15]
	v_and_b32_e32 v21, 0x3ffffff, v21
	v_and_b32_e32 v20, -4, v20
	v_and_b32_e32 v25, 0x3ffffff, v25
	v_and_b32_e32 v24, -4, v24
	v_lshl_add_u64 v[14:15], s[6:7], 0, v[16:17]
	global_load_dwordx2 v[12:13], v[6:7], off
	v_lshl_add_u64 v[26:27], v[6:7], 0, s[16:17]
	global_load_dwordx2 v[18:19], v[18:19], off
	v_lshl_add_u64 v[16:17], s[6:7], 0, v[20:21]
	global_load_dwordx2 v[22:23], v[22:23], off
	v_lshl_add_u64 v[20:21], s[6:7], 0, v[24:25]
	global_load_dword v34, v[14:15], off
	global_load_dword v35, v[16:17], off
	global_load_dword v36, v[20:21], off
	global_load_dwordx2 v[24:25], v[26:27], off
	v_lshl_add_u64 v[4:5], v[4:5], 0, s[26:27]
	v_lshl_add_u64 v[14:15], s[12:13], 0, v[4:5]
	v_cmp_lt_u64_e32 vcc, s[34:35], v[14:15]
	s_or_b64 s[28:29], vcc, s[28:29]
	v_lshl_add_u64 v[26:27], v[8:9], 0, s[14:15]
	v_lshl_add_u64 v[28:29], v[8:9], 0, s[18:19]
	v_lshl_add_u64 v[30:31], v[8:9], 0, s[24:25]
	v_lshl_add_u64 v[6:7], v[6:7], 0, s[18:19]
	v_mov_b64_e32 v[42:43], v[8:9]
	v_lshl_add_u64 v[8:9], v[8:9], 0, s[22:23]
	s_cmp_lg_u64 s[28:29], 0
	s_cbranch_scc1 .Lnp_finalA
	v_lshrrev_b64 v[54:55], 6, v[4:5]
	v_and_b32_e32 v55, 0x3ffffff, v55
	v_and_b32_e32 v54, -4, v54
	v_lshl_add_u64 v[56:57], s[8:9], 0, v[4:5]
	v_lshl_add_u64 v[54:55], s[6:7], 0, v[54:55]
	v_lshl_add_u64 v[60:61], s[30:31], 0, v[4:5]
	v_lshl_add_u64 v[64:65], s[12:13], 0, v[4:5]
	v_lshrrev_b64 v[56:57], 6, v[56:57]
	global_load_dword v51, v[54:55], off
	v_lshrrev_b64 v[60:61], 6, v[60:61]
	v_lshrrev_b64 v[64:65], 6, v[64:65]
	v_and_b32_e32 v57, 0x3ffffff, v57
	v_and_b32_e32 v56, -4, v56
	v_lshl_add_u64 v[58:59], v[6:7], 0, s[20:21]
	v_lshl_add_u64 v[62:63], v[6:7], 0, s[14:15]
	v_and_b32_e32 v61, 0x3ffffff, v61
	v_and_b32_e32 v60, -4, v60
	v_and_b32_e32 v65, 0x3ffffff, v65
	v_and_b32_e32 v64, -4, v64
	v_lshl_add_u64 v[54:55], s[6:7], 0, v[56:57]
	global_load_dwordx2 v[52:53], v[6:7], off
	v_lshl_add_u64 v[66:67], v[6:7], 0, s[16:17]
	global_load_dwordx2 v[58:59], v[58:59], off
	v_lshl_add_u64 v[56:57], s[6:7], 0, v[60:61]
	global_load_dwordx2 v[62:63], v[62:63], off
	v_lshl_add_u64 v[60:61], s[6:7], 0, v[64:65]
	global_load_dword v74, v[54:55], off
	global_load_dword v75, v[56:57], off
	global_load_dword v76, v[60:61], off
	global_load_dwordx2 v[64:65], v[66:67], off
	v_lshl_add_u64 v[4:5], v[4:5], 0, s[26:27]
	v_lshl_add_u64 v[54:55], s[12:13], 0, v[4:5]
	v_cmp_lt_u64_e32 vcc, s[34:35], v[54:55]
	s_or_b64 s[28:29], vcc, s[28:29]
	v_lshl_add_u64 v[66:67], v[8:9], 0, s[14:15]
	v_lshl_add_u64 v[68:69], v[8:9], 0, s[18:19]
	v_lshl_add_u64 v[70:71], v[8:9], 0, s[24:25]
	v_lshl_add_u64 v[6:7], v[6:7], 0, s[18:19]
	v_mov_b64_e32 v[82:83], v[8:9]
	v_lshl_add_u64 v[8:9], v[8:9], 0, s[22:23]
	s_waitcnt vmcnt(15)
	v_fmamk_f32 v11, v11, 0x3a800000, v10
	v_mul_f32_e32 v37, 0x4b800000, v11
	v_cmp_gt_f32_e32 vcc, s33, v11
	s_waitcnt vmcnt(14)
	v_lshlrev_b32_e32 v14, 16, v12
	v_cndmask_b32_e32 v11, v11, v37, vcc
	v_rsq_f32_e32 v11, v11
	s_waitcnt vmcnt(11)
	v_fmamk_f32 v34, v34, 0x3a800000, v10
	s_waitcnt vmcnt(10)
	v_fmamk_f32 v35, v35, 0x3a800000, v10
	s_waitcnt vmcnt(9)
	v_fmamk_f32 v36, v36, 0x3a800000, v10
	v_mul_f32_e32 v37, 0x4b800000, v34
	v_cmp_gt_f32_e64 s[0:1], s33, v34
	v_mul_f32_e32 v38, 0x4b800000, v35
	v_cmp_gt_f32_e64 s[2:3], s33, v35
	v_mul_f32_e32 v39, 0x4b800000, v36
	v_cmp_gt_f32_e64 s[4:5], s33, v36
	v_cndmask_b32_e64 v34, v34, v37, s[0:1]
	v_cndmask_b32_e64 v35, v35, v38, s[2:3]
	v_cndmask_b32_e64 v36, v36, v39, s[4:5]
	v_rsq_f32_e32 v38, v34
	v_rsq_f32_e32 v35, v35
	v_rsq_f32_e32 v39, v36
	v_mul_f32_e32 v34, 0x45800000, v11
	v_and_b32_e32 v15, 0xffff0000, v12
	v_lshlrev_b32_e32 v12, 16, v13
	v_and_b32_e32 v13, 0xffff0000, v13
	v_cndmask_b32_e32 v34, v11, v34, vcc
	v_mul_f32_e32 v11, 0x45800000, v38
	v_lshlrev_b32_e32 v16, 16, v18
	v_and_b32_e32 v17, 0xffff0000, v18
	v_lshlrev_b32_e32 v18, 16, v19
	v_and_b32_e32 v19, 0xffff0000, v19
	v_mul_f32_e32 v40, 0x45800000, v35
	v_mul_f32_e32 v41, 0x45800000, v39
	v_pk_mul_f32 v[36:37], v[34:35], v[14:15] op_sel_hi:[0,1]
	v_pk_mul_f32 v[12:13], v[34:35], v[12:13] op_sel_hi:[0,1]
	v_cndmask_b32_e64 v34, v38, v11, s[0:1]
	v_lshlrev_b32_e32 v20, 16, v22
	v_and_b32_e32 v21, 0xffff0000, v22
	v_lshlrev_b32_e32 v22, 16, v23
	v_and_b32_e32 v23, 0xffff0000, v23
	s_waitcnt vmcnt(8)
	v_lshlrev_b32_e32 v32, 16, v24
	v_and_b32_e32 v33, 0xffff0000, v24
	v_lshlrev_b32_e32 v24, 16, v25
	v_and_b32_e32 v25, 0xffff0000, v25
	v_cndmask_b32_e64 v38, v35, v40, s[2:3]
	v_cndmask_b32_e64 v40, v39, v41, s[4:5]
	v_pk_mul_f32 v[14:15], v[2:3], v[12:13]
	v_pk_mul_f32 v[12:13], v[0:1], v[36:37]
	v_pk_mul_f32 v[16:17], v[34:35], v[16:17] op_sel_hi:[0,1]
	v_pk_mul_f32 v[18:19], v[34:35], v[18:19] op_sel_hi:[0,1]
	v_pk_mul_f32 v[20:21], v[38:39], v[20:21] op_sel_hi:[0,1]
	v_pk_mul_f32 v[22:23], v[38:39], v[22:23] op_sel_hi:[0,1]
	v_pk_mul_f32 v[32:33], v[40:41], v[32:33] op_sel_hi:[0,1]
	v_pk_mul_f32 v[24:25], v[40:41], v[24:25] op_sel_hi:[0,1]
	global_store_dwordx4 v[42:43], v[12:15], off
	s_nop 0
	s_nop 0
	v_pk_mul_f32 v[14:15], v[2:3], v[18:19]
	v_pk_mul_f32 v[12:13], v[0:1], v[16:17]
	v_pk_mul_f32 v[18:19], v[2:3], v[22:23]
	v_pk_mul_f32 v[16:17], v[0:1], v[20:21]
	v_pk_mul_f32 v[22:23], v[2:3], v[24:25]
	v_pk_mul_f32 v[20:21], v[0:1], v[32:33]
	global_store_dwordx4 v[26:27], v[12:15], off
	global_store_dwordx4 v[28:29], v[16:19], off
	global_store_dwordx4 v[30:31], v[20:23], off
.Lnp_loop:
	s_cmp_lg_u64 s[28:29], 0
	s_cbranch_scc1 .Lnp_finalB
	v_lshrrev_b64 v[14:15], 6, v[4:5]
	v_and_b32_e32 v15, 0x3ffffff, v15
	v_and_b32_e32 v14, -4, v14
	v_lshl_add_u64 v[16:17], s[8:9], 0, v[4:5]
	v_lshl_add_u64 v[14:15], s[6:7], 0, v[14:15]
	v_lshl_add_u64 v[20:21], s[30:31], 0, v[4:5]
	v_lshl_add_u64 v[24:25], s[12:13], 0, v[4:5]
	v_lshrrev_b64 v[16:17], 6, v[16:17]
	global_load_dword v11, v[14:15], off
	v_lshrrev_b64 v[20:21], 6, v[20:21]
	v_lshrrev_b64 v[24:25], 6, v[24:25]
	v_and_b32_e32 v17, 0x3ffffff, v17
	v_and_b32_e32 v16, -4, v16
	v_lshl_add_u64 v[18:19], v[6:7], 0, s[20:21]
	v_lshl_add_u64 v[22:23], v[6:7], 0, s[14:15]
	v_and_b32_e32 v21, 0x3ffffff, v21
	v_and_b32_e32 v20, -4, v20
	v_and_b32_e32 v25, 0x3ffffff, v25
	v_and_b32_e32 v24, -4, v24
	v_lshl_add_u64 v[14:15], s[6:7], 0, v[16:17]
	global_load_dwordx2 v[12:13], v[6:7], off
	v_lshl_add_u64 v[26:27], v[6:7], 0, s[16:17]
	global_load_dwordx2 v[18:19], v[18:19], off
	v_lshl_add_u64 v[16:17], s[6:7], 0, v[20:21]
	global_load_dwordx2 v[22:23], v[22:23], off
	v_lshl_add_u64 v[20:21], s[6:7], 0, v[24:25]
	global_load_dword v34, v[14:15], off
	global_load_dword v35, v[16:17], off
	global_load_dword v36, v[20:21], off
	global_load_dwordx2 v[24:25], v[26:27], off
	v_lshl_add_u64 v[4:5], v[4:5], 0, s[26:27]
	v_lshl_add_u64 v[14:15], s[12:13], 0, v[4:5]
	v_cmp_lt_u64_e32 vcc, s[34:35], v[14:15]
	s_or_b64 s[28:29], vcc, s[28:29]
	v_lshl_add_u64 v[26:27], v[8:9], 0, s[14:15]
	v_lshl_add_u64 v[28:29], v[8:9], 0, s[18:19]
	v_lshl_add_u64 v[30:31], v[8:9], 0, s[24:25]
	v_lshl_add_u64 v[6:7], v[6:7], 0, s[18:19]
	v_mov_b64_e32 v[42:43], v[8:9]
	v_lshl_add_u64 v[8:9], v[8:9], 0, s[22:23]
	s_waitcnt vmcnt(19)
	v_fmamk_f32 v51, v51, 0x3a800000, v10
	v_mul_f32_e32 v77, 0x4b800000, v51
	v_cmp_gt_f32_e32 vcc, s33, v51
	s_waitcnt vmcnt(18)
	v_lshlrev_b32_e32 v54, 16, v52
	v_cndmask_b32_e32 v51, v51, v77, vcc
	v_rsq_f32_e32 v51, v51
	s_waitcnt vmcnt(15)
	v_fmamk_f32 v74, v74, 0x3a800000, v10
	s_waitcnt vmcnt(14)
	v_fmamk_f32 v75, v75, 0x3a800000, v10
	s_waitcnt vmcnt(13)
	v_fmamk_f32 v76, v76, 0x3a800000, v10
	v_mul_f32_e32 v77, 0x4b800000, v74
	v_cmp_gt_f32_e64 s[0:1], s33, v74
	v_mul_f32_e32 v78, 0x4b800000, v75
	v_cmp_gt_f32_e64 s[2:3], s33, v75
	v_mul_f32_e32 v79, 0x4b800000, v76
	v_cmp_gt_f32_e64 s[4:5], s33, v76
	v_cndmask_b32_e64 v74, v74, v77, s[0:1]
	v_cndmask_b32_e64 v75, v75, v78, s[2:3]
	v_cndmask_b32_e64 v76, v76, v79, s[4:5]
	v_rsq_f32_e32 v78, v74
	v_rsq_f32_e32 v75, v75
	v_rsq_f32_e32 v79, v76
	v_mul_f32_e32 v74, 0x45800000, v51
	v_and_b32_e32 v55, 0xffff0000, v52
	v_lshlrev_b32_e32 v52, 16, v53
	v_and_b32_e32 v53, 0xffff0000, v53
	v_cndmask_b32_e32 v74, v51, v74, vcc
	v_mul_f32_e32 v51, 0x45800000, v78
	v_lshlrev_b32_e32 v56, 16, v58
	v_and_b32_e32 v57, 0xffff0000, v58
	v_lshlrev_b32_e32 v58, 16, v59
	v_and_b32_e32 v59, 0xffff0000, v59
	v_mul_f32_e32 v80, 0x45800000, v75
	v_mul_f32_e32 v81, 0x45800000, v79
	v_pk_mul_f32 v[76:77], v[74:75], v[54:55] op_sel_hi:[0,1]
	v_pk_mul_f32 v[52:53], v[74:75], v[52:53] op_sel_hi:[0,1]
	v_cndmask_b32_e64 v74, v78, v51, s[0:1]
	v_lshlrev_b32_e32 v60, 16, v62
	v_and_b32_e32 v61, 0xffff0000, v62
	v_lshlrev_b32_e32 v62, 16, v63
	v_and_b32_e32 v63, 0xffff0000, v63
	s_waitcnt vmcnt(12)
	v_lshlrev_b32_e32 v72, 16, v64
	v_and_b32_e32 v73, 0xffff0000, v64
	v_lshlrev_b32_e32 v64, 16, v65
	v_and_b32_e32 v65, 0xffff0000, v65
	v_cndmask_b32_e64 v78, v75, v80, s[2:3]
	v_cndmask_b32_e64 v80, v79, v81, s[4:5]
	v_pk_mul_f32 v[54:55], v[2:3], v[52:53]
	v_pk_mul_f32 v[52:53], v[0:1], v[76:77]
	v_pk_mul_f32 v[56:57], v[74:75], v[56:57] op_sel_hi:[0,1]
	v_pk_mul_f32 v[58:59], v[74:75], v[58:59] op_sel_hi:[0,1]
	v_pk_mul_f32 v[60:61], v[78:79], v[60:61] op_sel_hi:[0,1]
	v_pk_mul_f32 v[62:63], v[78:79], v[62:63] op_sel_hi:[0,1]
	v_pk_mul_f32 v[72:73], v[80:81], v[72:73] op_sel_hi:[0,1]
	v_pk_mul_f32 v[64:65], v[80:81], v[64:65] op_sel_hi:[0,1]
	global_store_dwordx4 v[82:83], v[52:55], off
	s_nop 0
	s_nop 0
	v_pk_mul_f32 v[54:55], v[2:3], v[58:59]
	v_pk_mul_f32 v[52:53], v[0:1], v[56:57]
	v_pk_mul_f32 v[58:59], v[2:3], v[62:63]
	v_pk_mul_f32 v[56:57], v[0:1], v[60:61]
	v_pk_mul_f32 v[62:63], v[2:3], v[64:65]
	v_pk_mul_f32 v[60:61], v[0:1], v[72:73]
	global_store_dwordx4 v[66:67], v[52:55], off
	global_store_dwordx4 v[68:69], v[56:59], off
	global_store_dwordx4 v[70:71], v[60:63], off
	s_cmp_lg_u64 s[28:29], 0
	s_cbranch_scc1 .Lnp_finalA
	v_lshrrev_b64 v[54:55], 6, v[4:5]
	v_and_b32_e32 v55, 0x3ffffff, v55
	v_and_b32_e32 v54, -4, v54
	v_lshl_add_u64 v[56:57], s[8:9], 0, v[4:5]
	v_lshl_add_u64 v[54:55], s[6:7], 0, v[54:55]
	v_lshl_add_u64 v[60:61], s[30:31], 0, v[4:5]
	v_lshl_add_u64 v[64:65], s[12:13], 0, v[4:5]
	v_lshrrev_b64 v[56:57], 6, v[56:57]
	global_load_dword v51, v[54:55], off
	v_lshrrev_b64 v[60:61], 6, v[60:61]
	v_lshrrev_b64 v[64:65], 6, v[64:65]
	v_and_b32_e32 v57, 0x3ffffff, v57
	v_and_b32_e32 v56, -4, v56
	v_lshl_add_u64 v[58:59], v[6:7], 0, s[20:21]
	v_lshl_add_u64 v[62:63], v[6:7], 0, s[14:15]
	v_and_b32_e32 v61, 0x3ffffff, v61
	v_and_b32_e32 v60, -4, v60
	v_and_b32_e32 v65, 0x3ffffff, v65
	v_and_b32_e32 v64, -4, v64
	v_lshl_add_u64 v[54:55], s[6:7], 0, v[56:57]
	global_load_dwordx2 v[52:53], v[6:7], off
	v_lshl_add_u64 v[66:67], v[6:7], 0, s[16:17]
	global_load_dwordx2 v[58:59], v[58:59], off
	v_lshl_add_u64 v[56:57], s[6:7], 0, v[60:61]
	global_load_dwordx2 v[62:63], v[62:63], off
	v_lshl_add_u64 v[60:61], s[6:7], 0, v[64:65]
	global_load_dword v74, v[54:55], off
	global_load_dword v75, v[56:57], off
	global_load_dword v76, v[60:61], off
	global_load_dwordx2 v[64:65], v[66:67], off
	v_lshl_add_u64 v[4:5], v[4:5], 0, s[26:27]
	v_lshl_add_u64 v[54:55], s[12:13], 0, v[4:5]
	v_cmp_lt_u64_e32 vcc, s[34:35], v[54:55]
	s_or_b64 s[28:29], vcc, s[28:29]
	v_lshl_add_u64 v[66:67], v[8:9], 0, s[14:15]
	v_lshl_add_u64 v[68:69], v[8:9], 0, s[18:19]
	v_lshl_add_u64 v[70:71], v[8:9], 0, s[24:25]
	v_lshl_add_u64 v[6:7], v[6:7], 0, s[18:19]
	v_mov_b64_e32 v[82:83], v[8:9]
	v_lshl_add_u64 v[8:9], v[8:9], 0, s[22:23]
	s_waitcnt vmcnt(19)
	v_fmamk_f32 v11, v11, 0x3a800000, v10
	v_mul_f32_e32 v37, 0x4b800000, v11
	v_cmp_gt_f32_e32 vcc, s33, v11
	s_waitcnt vmcnt(18)
	v_lshlrev_b32_e32 v14, 16, v12
	v_cndmask_b32_e32 v11, v11, v37, vcc
	v_rsq_f32_e32 v11, v11
	s_waitcnt vmcnt(15)
	v_fmamk_f32 v34, v34, 0x3a800000, v10
	s_waitcnt vmcnt(14)
	v_fmamk_f32 v35, v35, 0x3a800000, v10
	s_waitcnt vmcnt(13)
	v_fmamk_f32 v36, v36, 0x3a800000, v10
	v_mul_f32_e32 v37, 0x4b800000, v34
	v_cmp_gt_f32_e64 s[0:1], s33, v34
	v_mul_f32_e32 v38, 0x4b800000, v35
	v_cmp_gt_f32_e64 s[2:3], s33, v35
	v_mul_f32_e32 v39, 0x4b800000, v36
	v_cmp_gt_f32_e64 s[4:5], s33, v36
	v_cndmask_b32_e64 v34, v34, v37, s[0:1]
	v_cndmask_b32_e64 v35, v35, v38, s[2:3]
	v_cndmask_b32_e64 v36, v36, v39, s[4:5]
	v_rsq_f32_e32 v38, v34
	v_rsq_f32_e32 v35, v35
	v_rsq_f32_e32 v39, v36
	v_mul_f32_e32 v34, 0x45800000, v11
	v_and_b32_e32 v15, 0xffff0000, v12
	v_lshlrev_b32_e32 v12, 16, v13
	v_and_b32_e32 v13, 0xffff0000, v13
	v_cndmask_b32_e32 v34, v11, v34, vcc
	v_mul_f32_e32 v11, 0x45800000, v38
	v_lshlrev_b32_e32 v16, 16, v18
	v_and_b32_e32 v17, 0xffff0000, v18
	v_lshlrev_b32_e32 v18, 16, v19
	v_and_b32_e32 v19, 0xffff0000, v19
	v_mul_f32_e32 v40, 0x45800000, v35
	v_mul_f32_e32 v41, 0x45800000, v39
	v_pk_mul_f32 v[36:37], v[34:35], v[14:15] op_sel_hi:[0,1]
	v_pk_mul_f32 v[12:13], v[34:35], v[12:13] op_sel_hi:[0,1]
	v_cndmask_b32_e64 v34, v38, v11, s[0:1]
	v_lshlrev_b32_e32 v20, 16, v22
	v_and_b32_e32 v21, 0xffff0000, v22
	v_lshlrev_b32_e32 v22, 16, v23
	v_and_b32_e32 v23, 0xffff0000, v23
	s_waitcnt vmcnt(12)
	v_lshlrev_b32_e32 v32, 16, v24
	v_and_b32_e32 v33, 0xffff0000, v24
	v_lshlrev_b32_e32 v24, 16, v25
	v_and_b32_e32 v25, 0xffff0000, v25
	v_cndmask_b32_e64 v38, v35, v40, s[2:3]
	v_cndmask_b32_e64 v40, v39, v41, s[4:5]
	v_pk_mul_f32 v[14:15], v[2:3], v[12:13]
	v_pk_mul_f32 v[12:13], v[0:1], v[36:37]
	v_pk_mul_f32 v[16:17], v[34:35], v[16:17] op_sel_hi:[0,1]
	v_pk_mul_f32 v[18:19], v[34:35], v[18:19] op_sel_hi:[0,1]
	v_pk_mul_f32 v[20:21], v[38:39], v[20:21] op_sel_hi:[0,1]
	v_pk_mul_f32 v[22:23], v[38:39], v[22:23] op_sel_hi:[0,1]
	v_pk_mul_f32 v[32:33], v[40:41], v[32:33] op_sel_hi:[0,1]
	v_pk_mul_f32 v[24:25], v[40:41], v[24:25] op_sel_hi:[0,1]
	global_store_dwordx4 v[42:43], v[12:15], off
	s_nop 0
	s_nop 0
	v_pk_mul_f32 v[14:15], v[2:3], v[18:19]
	v_pk_mul_f32 v[12:13], v[0:1], v[16:17]
	v_pk_mul_f32 v[18:19], v[2:3], v[22:23]
	v_pk_mul_f32 v[16:17], v[0:1], v[20:21]
	v_pk_mul_f32 v[22:23], v[2:3], v[24:25]
	v_pk_mul_f32 v[20:21], v[0:1], v[32:33]
	global_store_dwordx4 v[26:27], v[12:15], off
	global_store_dwordx4 v[28:29], v[16:19], off
	global_store_dwordx4 v[30:31], v[20:23], off
	s_branch .Lnp_loop
.Lnp_finalA:
	s_waitcnt vmcnt(7)
	v_fmamk_f32 v11, v11, 0x3a800000, v10
	v_mul_f32_e32 v37, 0x4b800000, v11
	v_cmp_gt_f32_e32 vcc, s33, v11
	s_waitcnt vmcnt(6)
	v_lshlrev_b32_e32 v14, 16, v12
	v_cndmask_b32_e32 v11, v11, v37, vcc
	v_rsq_f32_e32 v11, v11
	s_waitcnt vmcnt(3)
	v_fmamk_f32 v34, v34, 0x3a800000, v10
	s_waitcnt vmcnt(2)
	v_fmamk_f32 v35, v35, 0x3a800000, v10
	s_waitcnt vmcnt(1)
	v_fmamk_f32 v36, v36, 0x3a800000, v10
	v_mul_f32_e32 v37, 0x4b800000, v34
	v_cmp_gt_f32_e64 s[0:1], s33, v34
	v_mul_f32_e32 v38, 0x4b800000, v35
	v_cmp_gt_f32_e64 s[2:3], s33, v35
	v_mul_f32_e32 v39, 0x4b800000, v36
	v_cmp_gt_f32_e64 s[4:5], s33, v36
	v_cndmask_b32_e64 v34, v34, v37, s[0:1]
	v_cndmask_b32_e64 v35, v35, v38, s[2:3]
	v_cndmask_b32_e64 v36, v36, v39, s[4:5]
	v_rsq_f32_e32 v38, v34
	v_rsq_f32_e32 v35, v35
	v_rsq_f32_e32 v39, v36
	v_mul_f32_e32 v34, 0x45800000, v11
	v_and_b32_e32 v15, 0xffff0000, v12
	v_lshlrev_b32_e32 v12, 16, v13
	v_and_b32_e32 v13, 0xffff0000, v13
	v_cndmask_b32_e32 v34, v11, v34, vcc
	v_mul_f32_e32 v11, 0x45800000, v38
	v_lshlrev_b32_e32 v16, 16, v18
	v_and_b32_e32 v17, 0xffff0000, v18
	v_lshlrev_b32_e32 v18, 16, v19
	v_and_b32_e32 v19, 0xffff0000, v19
	v_mul_f32_e32 v40, 0x45800000, v35
	v_mul_f32_e32 v41, 0x45800000, v39
	v_pk_mul_f32 v[36:37], v[34:35], v[14:15] op_sel_hi:[0,1]
	v_pk_mul_f32 v[12:13], v[34:35], v[12:13] op_sel_hi:[0,1]
	v_cndmask_b32_e64 v34, v38, v11, s[0:1]
	v_lshlrev_b32_e32 v20, 16, v22
	v_and_b32_e32 v21, 0xffff0000, v22
	v_lshlrev_b32_e32 v22, 16, v23
	v_and_b32_e32 v23, 0xffff0000, v23
	s_waitcnt vmcnt(0)
	v_lshlrev_b32_e32 v32, 16, v24
	v_and_b32_e32 v33, 0xffff0000, v24
	v_lshlrev_b32_e32 v24, 16, v25
	v_and_b32_e32 v25, 0xffff0000, v25
	v_cndmask_b32_e64 v38, v35, v40, s[2:3]
	v_cndmask_b32_e64 v40, v39, v41, s[4:5]
	v_pk_mul_f32 v[14:15], v[2:3], v[12:13]
	v_pk_mul_f32 v[12:13], v[0:1], v[36:37]
	v_pk_mul_f32 v[16:17], v[34:35], v[16:17] op_sel_hi:[0,1]
	v_pk_mul_f32 v[18:19], v[34:35], v[18:19] op_sel_hi:[0,1]
	v_pk_mul_f32 v[20:21], v[38:39], v[20:21] op_sel_hi:[0,1]
	v_pk_mul_f32 v[22:23], v[38:39], v[22:23] op_sel_hi:[0,1]
	v_pk_mul_f32 v[32:33], v[40:41], v[32:33] op_sel_hi:[0,1]
	v_pk_mul_f32 v[24:25], v[40:41], v[24:25] op_sel_hi:[0,1]
	global_store_dwordx4 v[42:43], v[12:15], off
	s_nop 0
	s_nop 0
	v_pk_mul_f32 v[14:15], v[2:3], v[18:19]
	v_pk_mul_f32 v[12:13], v[0:1], v[16:17]
	v_pk_mul_f32 v[18:19], v[2:3], v[22:23]
	v_pk_mul_f32 v[16:17], v[0:1], v[20:21]
	v_pk_mul_f32 v[22:23], v[2:3], v[24:25]
	v_pk_mul_f32 v[20:21], v[0:1], v[32:33]
	global_store_dwordx4 v[26:27], v[12:15], off
	global_store_dwordx4 v[28:29], v[16:19], off
	global_store_dwordx4 v[30:31], v[20:23], off
	s_branch .Lnp_done
.Lnp_finalB:
	s_waitcnt vmcnt(7)
	v_fmamk_f32 v51, v51, 0x3a800000, v10
	v_mul_f32_e32 v77, 0x4b800000, v51
	v_cmp_gt_f32_e32 vcc, s33, v51
	s_waitcnt vmcnt(6)
	v_lshlrev_b32_e32 v54, 16, v52
	v_cndmask_b32_e32 v51, v51, v77, vcc
	v_rsq_f32_e32 v51, v51
	s_waitcnt vmcnt(3)
	v_fmamk_f32 v74, v74, 0x3a800000, v10
	s_waitcnt vmcnt(2)
	v_fmamk_f32 v75, v75, 0x3a800000, v10
	s_waitcnt vmcnt(1)
	v_fmamk_f32 v76, v76, 0x3a800000, v10
	v_mul_f32_e32 v77, 0x4b800000, v74
	v_cmp_gt_f32_e64 s[0:1], s33, v74
	v_mul_f32_e32 v78, 0x4b800000, v75
	v_cmp_gt_f32_e64 s[2:3], s33, v75
	v_mul_f32_e32 v79, 0x4b800000, v76
	v_cmp_gt_f32_e64 s[4:5], s33, v76
	v_cndmask_b32_e64 v74, v74, v77, s[0:1]
	v_cndmask_b32_e64 v75, v75, v78, s[2:3]
	v_cndmask_b32_e64 v76, v76, v79, s[4:5]
	v_rsq_f32_e32 v78, v74
	v_rsq_f32_e32 v75, v75
	v_rsq_f32_e32 v79, v76
	v_mul_f32_e32 v74, 0x45800000, v51
	v_and_b32_e32 v55, 0xffff0000, v52
	v_lshlrev_b32_e32 v52, 16, v53
	v_and_b32_e32 v53, 0xffff0000, v53
	v_cndmask_b32_e32 v74, v51, v74, vcc
	v_mul_f32_e32 v51, 0x45800000, v78
	v_lshlrev_b32_e32 v56, 16, v58
	v_and_b32_e32 v57, 0xffff0000, v58
	v_lshlrev_b32_e32 v58, 16, v59
	v_and_b32_e32 v59, 0xffff0000, v59
	v_mul_f32_e32 v80, 0x45800000, v75
	v_mul_f32_e32 v81, 0x45800000, v79
	v_pk_mul_f32 v[76:77], v[74:75], v[54:55] op_sel_hi:[0,1]
	v_pk_mul_f32 v[52:53], v[74:75], v[52:53] op_sel_hi:[0,1]
	v_cndmask_b32_e64 v74, v78, v51, s[0:1]
	v_lshlrev_b32_e32 v60, 16, v62
	v_and_b32_e32 v61, 0xffff0000, v62
	v_lshlrev_b32_e32 v62, 16, v63
	v_and_b32_e32 v63, 0xffff0000, v63
	s_waitcnt vmcnt(0)
	v_lshlrev_b32_e32 v72, 16, v64
	v_and_b32_e32 v73, 0xffff0000, v64
	v_lshlrev_b32_e32 v64, 16, v65
	v_and_b32_e32 v65, 0xffff0000, v65
	v_cndmask_b32_e64 v78, v75, v80, s[2:3]
	v_cndmask_b32_e64 v80, v79, v81, s[4:5]
	v_pk_mul_f32 v[54:55], v[2:3], v[52:53]
	v_pk_mul_f32 v[52:53], v[0:1], v[76:77]
	v_pk_mul_f32 v[56:57], v[74:75], v[56:57] op_sel_hi:[0,1]
	v_pk_mul_f32 v[58:59], v[74:75], v[58:59] op_sel_hi:[0,1]
	v_pk_mul_f32 v[60:61], v[78:79], v[60:61] op_sel_hi:[0,1]
	v_pk_mul_f32 v[62:63], v[78:79], v[62:63] op_sel_hi:[0,1]
	v_pk_mul_f32 v[72:73], v[80:81], v[72:73] op_sel_hi:[0,1]
	v_pk_mul_f32 v[64:65], v[80:81], v[64:65] op_sel_hi:[0,1]
	global_store_dwordx4 v[82:83], v[52:55], off
	s_nop 0
	s_nop 0
	v_pk_mul_f32 v[54:55], v[2:3], v[58:59]
	v_pk_mul_f32 v[52:53], v[0:1], v[56:57]
	v_pk_mul_f32 v[58:59], v[2:3], v[62:63]
	v_pk_mul_f32 v[56:57], v[0:1], v[60:61]
	v_pk_mul_f32 v[62:63], v[2:3], v[64:65]
	v_pk_mul_f32 v[60:61], v[0:1], v[72:73]
	global_store_dwordx4 v[66:67], v[52:55], off
	global_store_dwordx4 v[68:69], v[56:59], off
	global_store_dwordx4 v[70:71], v[60:63], off
.Lnp_done:
	s_or_b64 exec, exec, s[28:29]
